# attention C rescheduled loop: row sums with scalar v_add_f32 instead of v_pk_add_f32 beside the MFMAs
# baseline (speedup 1.0000x reference)
.LBB0_742:
	ds_read_b128 v[96:99], v240 offset:17408
	ds_read_b128 v[144:147], v240 offset:26112
	ds_read_b128 v[148:151], v240 offset:17440
	ds_read_b128 v[152:155], v240 offset:26144
	ds_read_b128 v[156:159], v240 offset:17472
	ds_read_b128 v[228:231], v240 offset:26176
	global_load_dwordx4 v[184:187], v247, s[100:101]
	global_load_dwordx4 v[188:191], v252, s[100:101]
	s_waitcnt lgkmcnt(5)
	v_mfma_f32_32x32x16_bf16 v[112:127], v[96:99], v[160:163], 0
	v_exp_f32_e32 v80, v80
	v_exp_f32_e32 v81, v81
	s_waitcnt lgkmcnt(4)
	v_mfma_f32_32x32x16_bf16 v[96:111], v[144:147], v[160:163], 0
	ds_read_b128 v[144:147], v240 offset:17504
	v_exp_f32_e32 v82, v82
	v_exp_f32_e32 v83, v83
	s_waitcnt lgkmcnt(4)
	v_mfma_f32_32x32x16_bf16 v[112:127], v[148:151], v[164:167], v[112:127]
	ds_read_b128 v[148:151], v240 offset:26208
	v_exp_f32_e32 v84, v84
	v_exp_f32_e32 v85, v85
	s_waitcnt lgkmcnt(4)
	v_mfma_f32_32x32x16_bf16 v[96:111], v[152:155], v[164:167], v[96:111]
	v_exp_f32_e32 v86, v86
	v_exp_f32_e32 v87, v87
	v_cvt_pk_bf16_f32 v128, v80, v81
	v_cvt_pk_bf16_f32 v129, v82, v83
	s_waitcnt lgkmcnt(3)
	v_mfma_f32_32x32x16_bf16 v[112:127], v[156:159], v[168:171], v[112:127]
	ds_read_b64_tr_b16 v[152:153], v207 offset:34816
	ds_read_b64_tr_b16 v[154:155], v207 offset:37376
	v_exp_f32_e32 v88, v88
	v_exp_f32_e32 v89, v89
	v_cvt_pk_bf16_f32 v130, v84, v85
	v_cvt_pk_bf16_f32 v131, v86, v87
	s_waitcnt lgkmcnt(4)
	v_mfma_f32_32x32x16_bf16 v[96:111], v[228:231], v[168:171], v[96:111]
	ds_read_b64_tr_b16 v[156:157], v207 offset:34880
	ds_read_b64_tr_b16 v[158:159], v207 offset:37440
	v_exp_f32_e32 v90, v90
	v_exp_f32_e32 v91, v91
	s_waitcnt lgkmcnt(5)
	v_mfma_f32_32x32x16_bf16 v[112:127], v[144:147], v[172:175], v[112:127]
	ds_read_b64_tr_b16 v[228:229], v207 offset:34944
	ds_read_b64_tr_b16 v[230:231], v207 offset:37504
	v_exp_f32_e32 v92, v92
	v_exp_f32_e32 v93, v93
	s_waitcnt lgkmcnt(6)
	v_mfma_f32_32x32x16_bf16 v[96:111], v[148:151], v[172:175], v[96:111]
	ds_read_b64_tr_b16 v[144:145], v207 offset:35008
	ds_read_b64_tr_b16 v[146:147], v207 offset:37568
	v_exp_f32_e32 v94, v94
	v_exp_f32_e32 v95, v95
	v_cvt_pk_bf16_f32 v132, v88, v89
	v_cvt_pk_bf16_f32 v133, v90, v91
	s_waitcnt lgkmcnt(6)
	v_mfma_f32_32x32x16_bf16 v[48:63], v[152:155], v[128:131], v[48:63]
	ds_read_b64_tr_b16 v[148:149], v207 offset:39936
	ds_read_b64_tr_b16 v[150:151], v207 offset:42496
	v_cvt_pk_bf16_f32 v134, v92, v93
	v_cvt_pk_bf16_f32 v135, v94, v95
	v_exp_f32_e32 v64, v64
	v_exp_f32_e32 v65, v65
	s_waitcnt lgkmcnt(6)
	v_mfma_f32_32x32x16_bf16 v[32:47], v[156:159], v[128:131], v[32:47]
	ds_read_b64_tr_b16 v[152:153], v207 offset:40000
	ds_read_b64_tr_b16 v[154:155], v207 offset:42560
	v_exp_f32_e32 v66, v66
	v_exp_f32_e32 v67, v67
	s_waitcnt lgkmcnt(6)
	v_mfma_f32_32x32x16_bf16 v[16:31], v[228:231], v[128:131], v[16:31]
	ds_read_b64_tr_b16 v[156:157], v207 offset:40064
	ds_read_b64_tr_b16 v[158:159], v207 offset:42624
	v_exp_f32_e32 v68, v68
	v_exp_f32_e32 v69, v69
	s_waitcnt lgkmcnt(6)
	v_mfma_f32_32x32x16_bf16 v[0:15], v[144:147], v[128:131], v[0:15]
	ds_read_b64_tr_b16 v[228:229], v207 offset:40128
	ds_read_b64_tr_b16 v[230:231], v207 offset:42688
	v_exp_f32_e32 v70, v70
	v_exp_f32_e32 v71, v71
	s_waitcnt lgkmcnt(6)
	v_mfma_f32_32x32x16_bf16 v[48:63], v[148:151], v[132:135], v[48:63]
	ds_read_b64_tr_b16 v[144:145], v207 offset:45056
	ds_read_b64_tr_b16 v[146:147], v207 offset:47616
	v_cvt_pk_bf16_f32 v136, v64, v65
	v_cvt_pk_bf16_f32 v137, v66, v67
	v_cvt_pk_bf16_f32 v138, v68, v69
	v_cvt_pk_bf16_f32 v139, v70, v71
	v_exp_f32_e32 v72, v72
	s_waitcnt lgkmcnt(6)
	v_mfma_f32_32x32x16_bf16 v[32:47], v[152:155], v[132:135], v[32:47]
	ds_read_b64_tr_b16 v[148:149], v207 offset:45120
	ds_read_b64_tr_b16 v[150:151], v207 offset:47680
	v_exp_f32_e32 v73, v73
	v_exp_f32_e32 v74, v74
	s_waitcnt lgkmcnt(6)
	v_mfma_f32_32x32x16_bf16 v[16:31], v[156:159], v[132:135], v[16:31]
	ds_read_b64_tr_b16 v[152:153], v207 offset:45184
	ds_read_b64_tr_b16 v[154:155], v207 offset:47744
	v_exp_f32_e32 v75, v75
	v_exp_f32_e32 v76, v76
	s_waitcnt lgkmcnt(6)
	v_mfma_f32_32x32x16_bf16 v[0:15], v[228:231], v[132:135], v[0:15]
	ds_read_b64_tr_b16 v[156:157], v207 offset:45248
	ds_read_b64_tr_b16 v[158:159], v207 offset:47808
	v_exp_f32_e32 v77, v77
	v_exp_f32_e32 v78, v78
	s_waitcnt lgkmcnt(6)
	v_mfma_f32_32x32x16_bf16 v[48:63], v[144:147], v[136:139], v[48:63]
	ds_read_b64_tr_b16 v[228:229], v207 offset:50176
	ds_read_b64_tr_b16 v[230:231], v207 offset:52736
	v_exp_f32_e32 v79, v79
	v_cvt_pk_bf16_f32 v140, v72, v73
	v_cvt_pk_bf16_f32 v141, v74, v75
	v_cvt_pk_bf16_f32 v142, v76, v77
	s_waitcnt lgkmcnt(6)
	v_mfma_f32_32x32x16_bf16 v[32:47], v[148:151], v[136:139], v[32:47]
	ds_read_b64_tr_b16 v[144:145], v207 offset:50240
	ds_read_b64_tr_b16 v[146:147], v207 offset:52800
	v_cvt_pk_bf16_f32 v143, v78, v79
	v_add_f32_e32 v80, v80, v82
	v_add_f32_e32 v81, v81, v83
	v_add_f32_e32 v84, v84, v86
	v_add_f32_e32 v85, v85, v87
	v_add_f32_e32 v88, v88, v90
	v_add_f32_e32 v89, v89, v91
	v_add_f32_e32 v92, v92, v94
	v_add_f32_e32 v93, v93, v95
	s_waitcnt lgkmcnt(6)
	v_mfma_f32_32x32x16_bf16 v[16:31], v[152:155], v[136:139], v[16:31]
	ds_read_b64_tr_b16 v[148:149], v207 offset:50304
	ds_read_b64_tr_b16 v[150:151], v207 offset:52864
	v_add_f32_e32 v64, v64, v66
	v_add_f32_e32 v65, v65, v67
	v_add_f32_e32 v68, v68, v70
	v_add_f32_e32 v69, v69, v71
	v_add_f32_e32 v72, v72, v74
	v_add_f32_e32 v73, v73, v75
	v_add_f32_e32 v76, v76, v78
	v_add_f32_e32 v77, v77, v79
	s_waitcnt lgkmcnt(6)
	v_mfma_f32_32x32x16_bf16 v[0:15], v[156:159], v[136:139], v[0:15]
	ds_read_b64_tr_b16 v[152:153], v207 offset:50368
	ds_read_b64_tr_b16 v[154:155], v207 offset:52928
	v_add_f32_e32 v80, v80, v84
	v_add_f32_e32 v81, v81, v85
	v_add_f32_e32 v88, v88, v92
	v_add_f32_e32 v89, v89, v93
	v_add_f32_e32 v64, v64, v68
	v_add_f32_e32 v65, v65, v69
	v_add_f32_e32 v72, v72, v76
	v_add_f32_e32 v73, v73, v77
	s_andn2_b64 vcc, exec, s[20:21]
	s_waitcnt lgkmcnt(6)
	v_mfma_f32_32x32x16_bf16 v[48:63], v[228:231], v[140:143], v[48:63]
	v_add_f32_e32 v80, v80, v88
	v_add_f32_e32 v81, v81, v89
	v_add_f32_e32 v64, v64, v72
	v_add_f32_e32 v65, v65, v73
	s_waitcnt lgkmcnt(4)
	v_mfma_f32_32x32x16_bf16 v[32:47], v[144:147], v[140:143], v[32:47]
	v_add_f32_e32 v64, v64, v80
	v_add_f32_e32 v65, v65, v81
	s_waitcnt lgkmcnt(2)
	v_mfma_f32_32x32x16_bf16 v[16:31], v[148:151], v[140:143], v[16:31]
	v_add_f32_e32 v64, v64, v65
	s_waitcnt lgkmcnt(0)
	v_mfma_f32_32x32x16_bf16 v[0:15], v[152:155], v[140:143], v[0:15]
	v_add_f32_e32 v246, v246, v64
	s_cbranch_vccnz .LBB0_746
	s_waitcnt vmcnt(3)
	ds_write_b128 v192, v[176:179]
	s_waitcnt vmcnt(2)
	ds_write_b128 v215, v[180:183]

.LBB0_751:
	s_waitcnt lgkmcnt(6)
	v_mfma_f32_32x32x16_bf16 v[48:63], v[152:155], v[128:131], v[48:63]
	ds_read_b64_tr_b16 v[148:149], v207 offset:60416
	ds_read_b64_tr_b16 v[150:151], v207 offset:62976
	v_cvt_pk_bf16_f32 v134, v124, v125
	v_cvt_pk_bf16_f32 v135, v126, v127
	v_exp_f32_e32 v96, v96
	v_exp_f32_e32 v97, v97
	s_waitcnt lgkmcnt(6)
	v_mfma_f32_32x32x16_bf16 v[32:47], v[156:159], v[128:131], v[32:47]
	ds_read_b64_tr_b16 v[152:153], v207 offset:60480
	ds_read_b64_tr_b16 v[154:155], v207 offset:63040
	v_exp_f32_e32 v98, v98
	v_exp_f32_e32 v99, v99
	s_waitcnt lgkmcnt(6)
	v_mfma_f32_32x32x16_bf16 v[16:31], v[228:231], v[128:131], v[16:31]
	ds_read_b64_tr_b16 v[156:157], v207 offset:60544
	ds_read_b64_tr_b16 v[158:159], v207 offset:63104
	v_exp_f32_e32 v100, v100
	v_exp_f32_e32 v101, v101
	s_waitcnt lgkmcnt(6)
	v_mfma_f32_32x32x16_bf16 v[0:15], v[144:147], v[128:131], v[0:15]
	ds_read_b64_tr_b16 v[228:229], v207 offset:60608
	ds_read_b64_tr_b16 v[230:231], v207 offset:63168
	v_exp_f32_e32 v102, v102
	v_exp_f32_e32 v103, v103
	s_waitcnt lgkmcnt(6)
	v_mfma_f32_32x32x16_bf16 v[48:63], v[148:151], v[132:135], v[48:63]
	ds_read_b64_tr_b16 v[144:145], v209 offset:10240
	ds_read_b64_tr_b16 v[146:147], v209 offset:12800
	v_cvt_pk_bf16_f32 v136, v96, v97
	v_cvt_pk_bf16_f32 v137, v98, v99
	v_cvt_pk_bf16_f32 v138, v100, v101
	v_cvt_pk_bf16_f32 v139, v102, v103
	v_exp_f32_e32 v104, v104
	s_waitcnt lgkmcnt(6)
	v_mfma_f32_32x32x16_bf16 v[32:47], v[152:155], v[132:135], v[32:47]
	ds_read_b64_tr_b16 v[148:149], v209 offset:10304
	ds_read_b64_tr_b16 v[150:151], v209 offset:12864
	v_exp_f32_e32 v105, v105
	v_exp_f32_e32 v106, v106
	s_waitcnt lgkmcnt(6)
	v_mfma_f32_32x32x16_bf16 v[16:31], v[156:159], v[132:135], v[16:31]
	ds_read_b64_tr_b16 v[152:153], v209 offset:10368
	ds_read_b64_tr_b16 v[154:155], v209 offset:12928
	v_exp_f32_e32 v107, v107
	v_exp_f32_e32 v108, v108
	s_waitcnt lgkmcnt(6)
	v_mfma_f32_32x32x16_bf16 v[0:15], v[228:231], v[132:135], v[0:15]
	ds_read_b64_tr_b16 v[156:157], v209 offset:10432
	ds_read_b64_tr_b16 v[158:159], v209 offset:12992
	v_exp_f32_e32 v109, v109
	v_exp_f32_e32 v110, v110
	s_waitcnt lgkmcnt(6)
	v_mfma_f32_32x32x16_bf16 v[48:63], v[144:147], v[136:139], v[48:63]
	ds_read_b64_tr_b16 v[228:229], v209 offset:15360
	ds_read_b64_tr_b16 v[230:231], v209 offset:17920
	v_exp_f32_e32 v111, v111
	v_cvt_pk_bf16_f32 v140, v104, v105
	v_cvt_pk_bf16_f32 v141, v106, v107
	v_cvt_pk_bf16_f32 v142, v108, v109
	s_waitcnt lgkmcnt(6)
	v_mfma_f32_32x32x16_bf16 v[32:47], v[148:151], v[136:139], v[32:47]
	ds_read_b64_tr_b16 v[144:145], v209 offset:15424
	ds_read_b64_tr_b16 v[146:147], v209 offset:17984
	v_cvt_pk_bf16_f32 v143, v110, v111
	v_add_f32_e32 v112, v112, v114
	v_add_f32_e32 v113, v113, v115
	v_add_f32_e32 v116, v116, v118
	v_add_f32_e32 v117, v117, v119
	v_add_f32_e32 v120, v120, v122
	v_add_f32_e32 v121, v121, v123
	v_add_f32_e32 v124, v124, v126
	v_add_f32_e32 v125, v125, v127
	s_waitcnt lgkmcnt(6)
	v_mfma_f32_32x32x16_bf16 v[16:31], v[152:155], v[136:139], v[16:31]
	ds_read_b64_tr_b16 v[148:149], v209 offset:15488
	ds_read_b64_tr_b16 v[150:151], v209 offset:18048
	v_add_f32_e32 v96, v96, v98
	v_add_f32_e32 v97, v97, v99
	v_add_f32_e32 v100, v100, v102
	v_add_f32_e32 v101, v101, v103
	v_add_f32_e32 v104, v104, v106
	v_add_f32_e32 v105, v105, v107
	v_add_f32_e32 v108, v108, v110
	v_add_f32_e32 v109, v109, v111
	s_waitcnt lgkmcnt(6)
	v_mfma_f32_32x32x16_bf16 v[0:15], v[156:159], v[136:139], v[0:15]
	ds_read_b64_tr_b16 v[152:153], v209 offset:15552
	ds_read_b64_tr_b16 v[154:155], v209 offset:18112
	v_add_f32_e32 v112, v112, v116
	v_add_f32_e32 v113, v113, v117
	v_add_f32_e32 v120, v120, v124
	v_add_f32_e32 v121, v121, v125
	v_add_f32_e32 v96, v96, v100
	v_add_f32_e32 v97, v97, v101
	v_add_f32_e32 v104, v104, v108
	v_add_f32_e32 v105, v105, v109
	s_andn2_b64 vcc, exec, s[20:21]
	s_waitcnt lgkmcnt(6)
	v_mfma_f32_32x32x16_bf16 v[48:63], v[228:231], v[140:143], v[48:63]
	v_add_f32_e32 v112, v112, v120
	v_add_f32_e32 v113, v113, v121
	v_add_f32_e32 v96, v96, v104
	v_add_f32_e32 v97, v97, v105
	s_waitcnt lgkmcnt(4)
	v_mfma_f32_32x32x16_bf16 v[32:47], v[144:147], v[140:143], v[32:47]
	v_add_f32_e32 v96, v96, v112
	v_add_f32_e32 v97, v97, v113
	s_waitcnt lgkmcnt(2)
	v_mfma_f32_32x32x16_bf16 v[16:31], v[148:151], v[140:143], v[16:31]
	v_add_f32_e32 v96, v96, v97
	s_waitcnt lgkmcnt(0)
	v_mfma_f32_32x32x16_bf16 v[0:15], v[152:155], v[140:143], v[0:15]
	v_add_f32_e32 v246, v246, v96
	s_cbranch_vccnz .LBB0_755
	s_waitcnt vmcnt(1)
	ds_write_b128 v241, v[176:179] offset:17408
	s_waitcnt vmcnt(0)
	ds_write_b128 v242, v[180:183] offset:17408
